# EpiConv: row statistics of the tile staged into LDS by LDS-DMA at the start of the tile K-loop and read with ds_read_b128 in the epilogue (8 exposed global loads per tile removed)
# speedup vs baseline: 1.0154x; 1.0154x over previous
.LBB0_452:
	s_ashr_i32 s99, s98, 31
	s_lshl_b64 s[28:29], s[98:99], 11
	s_add_u32 s94, s46, s28
	s_addc_u32 s95, s47, s29
	s_and_b64 s[28:29], s[20:21], exec
	s_cselect_b32 s30, s95, s23
	s_cselect_b32 s31, s94, s22
	s_ashr_i32 s81, s80, 31
	s_lshl_b64 s[28:29], s[80:81], 11
	v_readlane_b32 s62, v254, 3
	s_add_u32 s62, s62, s28
	v_readlane_b32 s28, v254, 4
	s_addc_u32 s63, s28, s29
	s_and_b64 s[28:29], s[20:21], exec
	s_cselect_b32 s69, s63, s25
	s_cselect_b32 s75, s62, s24
	s_add_u32 s22, s22, 0x40080
	s_addc_u32 s23, s23, 0
	s_add_u32 s81, s24, 0x100
	s_addc_u32 s99, s25, 0
	s_mov_b32 vcc_lo, -2
	v_readfirstlane_b32 s100, v237
	s_cmp_gt_u32 s100, 255
	s_cbranch_scc1 .Lmy_rs_skip
	s_lshl_b32 s32, s100, 4
	s_add_i32 s32, s32, 0x22000
	s_lshl_b32 s100, s73, 12
	v_lshlrev_b32_e32 v250, 4, v237
	s_mov_b32 m0, s32
	v_add_u32_e32 v250, s100, v250
	global_load_lds_dwordx4 v250, s[48:49]
.Lmy_rs_skip:
	s_add_u32 s24, s22, 0xfffc0080
	s_addc_u32 s25, s23, -1
	s_add_i32 s76, 0, 0x10000
	s_cmp_eq_u32 vcc_lo, 12
	s_cselect_b32 s29, s30, s25
	s_cselect_b32 s28, s31, s24
	v_add_u32_e32 v114, s76, v220
	s_cselect_b32 s25, s69, s99
	s_cselect_b32 s24, s75, s81
	s_add_i32 vcc_hi, 0, 0x14000
	ds_read_b128 v[106:109], v114
	ds_read_b128 v[110:113], v114 offset:1024
	ds_read_b128 v[128:131], v114 offset:2048
	ds_read_b128 v[132:135], v114 offset:3072
	v_add_u32_e32 v114, vcc_hi, v220
	ds_read_b128 v[136:139], v114
	ds_read_b128 v[158:161], v114 offset:1024
	ds_read_b128 v[162:165], v114 offset:2048
	ds_read_b128 v[166:169], v114 offset:3072
	s_add_i32 m0, s57, 0xc000
	ds_read_b128 v[170:173], v234
	ds_read_b128 v[174:177], v234 offset:1024
	ds_read_b128 v[178:181], v234 offset:2048
	ds_read_b128 v[198:201], v234 offset:3072
	ds_read_b128 v[202:205], v234 offset:4096
	ds_read_b128 v[206:209], v234 offset:5120
	ds_read_b128 v[210:213], v234 offset:6144
	ds_read_b128 v[214:217], v234 offset:7168
	global_load_lds_dwordx4 v194, s[22:23]
	s_add_i32 m0, s57, 0xe000
	s_nop 0
	global_load_lds_dwordx4 v196, s[22:23]
	s_waitcnt vmcnt(8)
	s_waitcnt lgkmcnt(0)
	s_barrier
	s_setprio 1
	v_mfma_f32_16x16x32_bf16 v[124:127], v[106:109], v[170:173], 0
	v_mfma_f32_16x16x32_bf16 v[98:101], v[128:131], v[170:173], 0
	v_mfma_f32_16x16x32_bf16 v[154:157], v[106:109], v[178:181], 0
	v_mfma_f32_16x16x32_bf16 v[58:61], v[128:131], v[178:181], 0
	v_mfma_f32_16x16x32_bf16 v[146:149], v[106:109], v[202:205], 0
	v_mfma_f32_16x16x32_bf16 v[46:49], v[128:131], v[202:205], 0
	v_mfma_f32_16x16x32_bf16 v[102:105], v[106:109], v[210:213], 0
	v_mfma_f32_16x16x32_bf16 v[54:57], v[128:131], v[210:213], 0
	v_mfma_f32_16x16x32_bf16 v[124:127], v[110:113], v[174:177], v[124:127]
	v_mfma_f32_16x16x32_bf16 v[98:101], v[132:135], v[174:177], v[98:101]
	v_mfma_f32_16x16x32_bf16 v[154:157], v[110:113], v[198:201], v[154:157]
	v_mfma_f32_16x16x32_bf16 v[58:61], v[132:135], v[198:201], v[58:61]
	v_mfma_f32_16x16x32_bf16 v[146:149], v[110:113], v[206:209], v[146:149]
	v_mfma_f32_16x16x32_bf16 v[46:49], v[132:135], v[206:209], v[46:49]
	v_mfma_f32_16x16x32_bf16 v[102:105], v[110:113], v[214:217], v[102:105]
	v_mfma_f32_16x16x32_bf16 v[54:57], v[132:135], v[214:217], v[54:57]
	v_mfma_f32_16x16x32_bf16 v[120:123], v[136:139], v[170:173], 0
	v_mfma_f32_16x16x32_bf16 v[94:97], v[162:165], v[170:173], 0
	v_mfma_f32_16x16x32_bf16 v[150:153], v[136:139], v[178:181], 0
	v_mfma_f32_16x16x32_bf16 v[50:53], v[162:165], v[178:181], 0
	v_mfma_f32_16x16x32_bf16 v[140:143], v[136:139], v[202:205], 0
	v_mfma_f32_16x16x32_bf16 v[42:45], v[162:165], v[202:205], 0
	v_mfma_f32_16x16x32_bf16 v[114:117], v[136:139], v[210:213], 0
	v_mfma_f32_16x16x32_bf16 v[38:41], v[162:165], v[210:213], 0
	v_mfma_f32_16x16x32_bf16 v[120:123], v[158:161], v[174:177], v[120:123]
	v_mfma_f32_16x16x32_bf16 v[94:97], v[166:169], v[174:177], v[94:97]
	v_mfma_f32_16x16x32_bf16 v[150:153], v[158:161], v[198:201], v[150:153]
	v_mfma_f32_16x16x32_bf16 v[50:53], v[166:169], v[198:201], v[50:53]
	v_mfma_f32_16x16x32_bf16 v[140:143], v[158:161], v[206:209], v[140:143]
	v_mfma_f32_16x16x32_bf16 v[42:45], v[166:169], v[206:209], v[42:45]
	v_mfma_f32_16x16x32_bf16 v[114:117], v[158:161], v[214:217], v[114:117]
	v_mfma_f32_16x16x32_bf16 v[38:41], v[166:169], v[214:217], v[38:41]
	s_setprio 0
	s_barrier
	s_add_i32 s76, s76, s42
	s_mov_b32 m0, s76
	ds_read_b128 v[170:173], v234 offset:16384
	ds_read_b128 v[174:177], v234 offset:17408
	ds_read_b128 v[178:181], v234 offset:18432
	ds_read_b128 v[198:201], v234 offset:19456
	ds_read_b128 v[202:205], v234 offset:20480
	ds_read_b128 v[206:209], v234 offset:21504
	ds_read_b128 v[210:213], v234 offset:22528
	ds_read_b128 v[214:217], v234 offset:23552
	global_load_lds_dwordx4 v0, s[24:25]
	s_add_i32 m0, s76, 0x2000
	s_add_u32 s76, s24, 0x40000
	s_addc_u32 s77, s25, 0
	s_add_i32 vcc_hi, vcc_hi, s42
	global_load_lds_dwordx4 v192, s[24:25]
	s_mov_b32 m0, vcc_hi
	s_nop 0
	global_load_lds_dwordx4 v0, s[76:77]
	s_add_i32 m0, vcc_hi, 0x2000
	s_nop 0
	global_load_lds_dwordx4 v192, s[76:77]
	s_mov_b32 m0, s57
	s_nop 0
	global_load_lds_dwordx4 v188, s[28:29]
	s_mov_b32 m0, s66
	s_nop 0
	global_load_lds_dwordx4 v190, s[28:29]
	s_waitcnt vmcnt(8)
	s_waitcnt lgkmcnt(0)
	s_barrier
	s_setprio 1
	v_mfma_f32_16x16x32_bf16 v[86:89], v[106:109], v[170:173], 0
	v_mfma_f32_16x16x32_bf16 v[30:33], v[128:131], v[170:173], 0
	v_mfma_f32_16x16x32_bf16 v[78:81], v[106:109], v[178:181], 0
	v_mfma_f32_16x16x32_bf16 v[22:25], v[128:131], v[178:181], 0
	v_mfma_f32_16x16x32_bf16 v[70:73], v[106:109], v[202:205], 0
	v_mfma_f32_16x16x32_bf16 v[14:17], v[128:131], v[202:205], 0
	v_mfma_f32_16x16x32_bf16 v[90:93], v[106:109], v[210:213], 0
	v_mfma_f32_16x16x32_bf16 v[34:37], v[128:131], v[210:213], 0
	v_mfma_f32_16x16x32_bf16 v[86:89], v[110:113], v[174:177], v[86:89]
	v_mfma_f32_16x16x32_bf16 v[30:33], v[132:135], v[174:177], v[30:33]
	v_mfma_f32_16x16x32_bf16 v[78:81], v[110:113], v[198:201], v[78:81]
	v_mfma_f32_16x16x32_bf16 v[22:25], v[132:135], v[198:201], v[22:25]
	v_mfma_f32_16x16x32_bf16 v[70:73], v[110:113], v[206:209], v[70:73]
	v_mfma_f32_16x16x32_bf16 v[14:17], v[132:135], v[206:209], v[14:17]
	v_mfma_f32_16x16x32_bf16 v[90:93], v[110:113], v[214:217], v[90:93]
	v_mfma_f32_16x16x32_bf16 v[34:37], v[132:135], v[214:217], v[34:37]
	v_mfma_f32_16x16x32_bf16 v[82:85], v[136:139], v[170:173], 0
	v_mfma_f32_16x16x32_bf16 v[26:29], v[162:165], v[170:173], 0
	v_mfma_f32_16x16x32_bf16 v[74:77], v[136:139], v[178:181], 0
	v_mfma_f32_16x16x32_bf16 v[18:21], v[162:165], v[178:181], 0
	v_mfma_f32_16x16x32_bf16 v[66:69], v[136:139], v[202:205], 0
	v_mfma_f32_16x16x32_bf16 v[10:13], v[162:165], v[202:205], 0
	v_mfma_f32_16x16x32_bf16 v[62:65], v[136:139], v[210:213], 0
	v_mfma_f32_16x16x32_bf16 v[6:9], v[162:165], v[210:213], 0
	v_mfma_f32_16x16x32_bf16 v[82:85], v[158:161], v[174:177], v[82:85]
	v_mfma_f32_16x16x32_bf16 v[26:29], v[166:169], v[174:177], v[26:29]
	v_mfma_f32_16x16x32_bf16 v[74:77], v[158:161], v[198:201], v[74:77]
	v_mfma_f32_16x16x32_bf16 v[18:21], v[166:169], v[198:201], v[18:21]
	v_mfma_f32_16x16x32_bf16 v[66:69], v[158:161], v[206:209], v[66:69]
	v_mfma_f32_16x16x32_bf16 v[10:13], v[166:169], v[206:209], v[10:13]
	v_mfma_f32_16x16x32_bf16 v[62:65], v[158:161], v[214:217], v[62:65]
	v_mfma_f32_16x16x32_bf16 v[6:9], v[166:169], v[214:217], v[6:9]
	s_setprio 0
	s_barrier
	s_add_i32 s76, 0, 0x18000
	v_add_u32_e32 v118, s76, v220
	s_add_i32 s77, 0, 0x1c000
	ds_read_b128 v[106:109], v118
	ds_read_b128 v[110:113], v118 offset:1024
	ds_read_b128 v[128:131], v118 offset:2048
	ds_read_b128 v[132:135], v118 offset:3072
	v_add_u32_e32 v118, s77, v220
	ds_read_b128 v[136:139], v118
	ds_read_b128 v[158:161], v118 offset:1024
	ds_read_b128 v[162:165], v118 offset:2048
	ds_read_b128 v[166:169], v118 offset:3072
	s_add_u32 s28, s28, 0x40000
	s_addc_u32 s29, s29, 0
	s_mov_b32 m0, s67
	ds_read_b128 v[170:173], v234 offset:32768
	ds_read_b128 v[174:177], v234 offset:33792
	ds_read_b128 v[178:181], v234 offset:34816
	ds_read_b128 v[198:201], v234 offset:35840
	ds_read_b128 v[202:205], v234 offset:36864
	ds_read_b128 v[206:209], v234 offset:37888
	ds_read_b128 v[210:213], v234 offset:38912
	ds_read_b128 v[214:217], v234 offset:39936
	global_load_lds_dwordx4 v188, s[28:29]
	s_mov_b32 m0, s44
	s_nop 0
	global_load_lds_dwordx4 v190, s[28:29]
	s_waitcnt vmcnt(8)
	s_waitcnt lgkmcnt(0)
	s_barrier
	s_setprio 1
	v_mfma_f32_16x16x32_bf16 v[124:127], v[106:109], v[170:173], v[124:127]
	v_mfma_f32_16x16x32_bf16 v[98:101], v[128:131], v[170:173], v[98:101]
	v_mfma_f32_16x16x32_bf16 v[154:157], v[106:109], v[178:181], v[154:157]
	v_mfma_f32_16x16x32_bf16 v[58:61], v[128:131], v[178:181], v[58:61]
	v_mfma_f32_16x16x32_bf16 v[144:147], v[106:109], v[202:205], v[146:149]
	v_mfma_f32_16x16x32_bf16 v[46:49], v[128:131], v[202:205], v[46:49]
	v_mfma_f32_16x16x32_bf16 v[102:105], v[106:109], v[210:213], v[102:105]
	v_mfma_f32_16x16x32_bf16 v[54:57], v[128:131], v[210:213], v[54:57]
	v_mfma_f32_16x16x32_bf16 v[124:127], v[110:113], v[174:177], v[124:127]
	v_mfma_f32_16x16x32_bf16 v[98:101], v[132:135], v[174:177], v[98:101]
	v_mfma_f32_16x16x32_bf16 v[154:157], v[110:113], v[198:201], v[154:157]
	v_mfma_f32_16x16x32_bf16 v[58:61], v[132:135], v[198:201], v[58:61]
	v_mfma_f32_16x16x32_bf16 v[146:149], v[110:113], v[206:209], v[144:147]
	v_mfma_f32_16x16x32_bf16 v[46:49], v[132:135], v[206:209], v[46:49]
	v_mfma_f32_16x16x32_bf16 v[102:105], v[110:113], v[214:217], v[102:105]
	v_mfma_f32_16x16x32_bf16 v[54:57], v[132:135], v[214:217], v[54:57]
	v_mfma_f32_16x16x32_bf16 v[118:121], v[136:139], v[170:173], v[120:123]
	v_mfma_f32_16x16x32_bf16 v[94:97], v[162:165], v[170:173], v[94:97]
	v_mfma_f32_16x16x32_bf16 v[150:153], v[136:139], v[178:181], v[150:153]
	v_mfma_f32_16x16x32_bf16 v[50:53], v[162:165], v[178:181], v[50:53]
	v_mfma_f32_16x16x32_bf16 v[140:143], v[136:139], v[202:205], v[140:143]
	v_mfma_f32_16x16x32_bf16 v[42:45], v[162:165], v[202:205], v[42:45]
	v_mfma_f32_16x16x32_bf16 v[114:117], v[136:139], v[210:213], v[114:117]
	v_mfma_f32_16x16x32_bf16 v[38:41], v[162:165], v[210:213], v[38:41]
	v_mfma_f32_16x16x32_bf16 v[120:123], v[158:161], v[174:177], v[118:121]
	v_mfma_f32_16x16x32_bf16 v[94:97], v[166:169], v[174:177], v[94:97]
	v_mfma_f32_16x16x32_bf16 v[150:153], v[158:161], v[198:201], v[150:153]
	v_mfma_f32_16x16x32_bf16 v[50:53], v[166:169], v[198:201], v[50:53]
	v_mfma_f32_16x16x32_bf16 v[142:145], v[158:161], v[206:209], v[140:143]
	v_mfma_f32_16x16x32_bf16 v[42:45], v[166:169], v[206:209], v[42:45]
	v_mfma_f32_16x16x32_bf16 v[116:119], v[158:161], v[214:217], v[114:117]
	v_mfma_f32_16x16x32_bf16 v[38:41], v[166:169], v[214:217], v[38:41]
	s_setprio 0
	s_barrier
	s_add_i32 s100, s76, s42
	s_mov_b32 m0, s100
	ds_read_b128 v[170:173], v234 offset:49152
	ds_read_b128 v[174:177], v234 offset:50176
	ds_read_b128 v[178:181], v234 offset:51200
	ds_read_b128 v[198:201], v234 offset:52224
	ds_read_b128 v[202:205], v234 offset:53248
	ds_read_b128 v[206:209], v234 offset:54272
	ds_read_b128 v[210:213], v234 offset:55296
	ds_read_b128 v[214:217], v234 offset:56320
	s_add_u32 s24, s24, 0x80
	s_addc_u32 s25, s25, 0
	global_load_lds_dwordx4 v0, s[24:25]
	s_add_i32 m0, s100, 0x2000
	s_add_i32 s100, s77, s42
	global_load_lds_dwordx4 v192, s[24:25]
	s_add_u32 s24, s24, 0x40000
	s_addc_u32 s25, s25, 0
	s_mov_b32 m0, s100
	s_add_i32 s100, s100, 0x2000
	global_load_lds_dwordx4 v0, s[24:25]
	s_mov_b32 m0, s100
	s_add_u32 s28, s28, 0xfffc0080
	s_addc_u32 s29, s29, -1
	global_load_lds_dwordx4 v192, s[24:25]
	s_mov_b32 m0, s45
	s_nop 0
	global_load_lds_dwordx4 v188, s[28:29]
	s_mov_b32 m0, s70
	s_nop 0
	global_load_lds_dwordx4 v190, s[28:29]
	s_waitcnt vmcnt(8)
	s_waitcnt lgkmcnt(0)
	s_barrier
	s_setprio 1
	v_mfma_f32_16x16x32_bf16 v[86:89], v[106:109], v[170:173], v[86:89]
	v_mfma_f32_16x16x32_bf16 v[30:33], v[128:131], v[170:173], v[30:33]
	v_mfma_f32_16x16x32_bf16 v[78:81], v[106:109], v[178:181], v[78:81]
	v_mfma_f32_16x16x32_bf16 v[22:25], v[128:131], v[178:181], v[22:25]
	v_mfma_f32_16x16x32_bf16 v[70:73], v[106:109], v[202:205], v[70:73]
	v_mfma_f32_16x16x32_bf16 v[14:17], v[128:131], v[202:205], v[14:17]
	v_mfma_f32_16x16x32_bf16 v[90:93], v[106:109], v[210:213], v[90:93]
	v_mfma_f32_16x16x32_bf16 v[34:37], v[128:131], v[210:213], v[34:37]
	v_mfma_f32_16x16x32_bf16 v[86:89], v[110:113], v[174:177], v[86:89]
	v_mfma_f32_16x16x32_bf16 v[30:33], v[132:135], v[174:177], v[30:33]
	v_mfma_f32_16x16x32_bf16 v[78:81], v[110:113], v[198:201], v[78:81]
	v_mfma_f32_16x16x32_bf16 v[22:25], v[132:135], v[198:201], v[22:25]
	v_mfma_f32_16x16x32_bf16 v[70:73], v[110:113], v[206:209], v[70:73]
	v_mfma_f32_16x16x32_bf16 v[14:17], v[132:135], v[206:209], v[14:17]
	v_mfma_f32_16x16x32_bf16 v[90:93], v[110:113], v[214:217], v[90:93]
	v_mfma_f32_16x16x32_bf16 v[34:37], v[132:135], v[214:217], v[34:37]
	v_mfma_f32_16x16x32_bf16 v[82:85], v[136:139], v[170:173], v[82:85]
	v_mfma_f32_16x16x32_bf16 v[26:29], v[162:165], v[170:173], v[26:29]
	v_mfma_f32_16x16x32_bf16 v[74:77], v[136:139], v[178:181], v[74:77]
	v_mfma_f32_16x16x32_bf16 v[18:21], v[162:165], v[178:181], v[18:21]
	v_mfma_f32_16x16x32_bf16 v[66:69], v[136:139], v[202:205], v[66:69]
	v_mfma_f32_16x16x32_bf16 v[10:13], v[162:165], v[202:205], v[10:13]
	v_mfma_f32_16x16x32_bf16 v[62:65], v[136:139], v[210:213], v[62:65]
	v_mfma_f32_16x16x32_bf16 v[6:9], v[162:165], v[210:213], v[6:9]
	v_mfma_f32_16x16x32_bf16 v[82:85], v[158:161], v[174:177], v[82:85]
	v_mfma_f32_16x16x32_bf16 v[26:29], v[166:169], v[174:177], v[26:29]
	v_mfma_f32_16x16x32_bf16 v[74:77], v[158:161], v[198:201], v[74:77]
	v_mfma_f32_16x16x32_bf16 v[18:21], v[166:169], v[198:201], v[18:21]
	v_mfma_f32_16x16x32_bf16 v[66:69], v[158:161], v[206:209], v[66:69]
	v_mfma_f32_16x16x32_bf16 v[10:13], v[166:169], v[206:209], v[10:13]
	v_mfma_f32_16x16x32_bf16 v[62:65], v[158:161], v[214:217], v[62:65]
	v_mfma_f32_16x16x32_bf16 v[6:9], v[166:169], v[214:217], v[6:9]
	s_setprio 0
	s_barrier
	s_add_i32 vcc_lo, vcc_lo, 2
	s_add_u32 s22, s22, 0x100
	s_addc_u32 s23, s23, 0
	s_add_u32 s81, s81, 0x100
	s_addc_u32 s99, s99, 0
	s_cmp_gt_u32 vcc_lo, 13
	s_cbranch_scc0 .LBB0_453

.LBB0_456:
	v_lshlrev_b32_e32 v251, 4, v219
	v_add_u32_e32 v251, 0x22000, v251
	s_lshl_b32 s81, s73, 8
	v_add_u32_e32 v210, s81, v219
	v_ashrrev_i32_e32 v211, 31, v210
	v_lshl_add_u64 v[106:107], v[210:211], 4, s[48:49]
	ds_read_b128 v[128:131], v251
	v_or_b32_e32 v106, 16, v210
	v_ashrrev_i32_e32 v107, 31, v106
	v_lshl_add_u64 v[106:107], v[106:107], 4, s[48:49]
	ds_read_b128 v[164:167], v251 offset:256
	v_or_b32_e32 v106, 32, v210
	v_ashrrev_i32_e32 v107, 31, v106
	v_lshl_add_u64 v[106:107], v[106:107], 4, s[48:49]
	ds_read_b128 v[160:163], v251 offset:512
	v_or_b32_e32 v106, 48, v210
	v_ashrrev_i32_e32 v107, 31, v106
	v_lshl_add_u64 v[106:107], v[106:107], 4, s[48:49]
	ds_read_b128 v[106:109], v251 offset:768
	v_add_u32_e32 v206, 0x80, v210
	v_add_u32_e32 v198, 0xb0, v210
	v_ashrrev_i32_e32 v207, 31, v206
	v_ashrrev_i32_e32 v199, 31, v198
	v_add_u32_e32 v204, 0x90, v210
	v_ashrrev_i32_e32 v205, 31, v204
	v_add_u32_e32 v200, 0xa0, v210
	v_ashrrev_i32_e32 v201, 31, v200
	v_lshl_or_b32 v212, s68, 7, v221
	s_waitcnt lgkmcnt(0)
	v_mov_b32_e32 v110, v107
	v_mov_b32_e32 v111, v108
	v_mov_b32_e32 v107, v109
	v_pk_add_f32 v[106:107], v[110:111], v[106:107]
	v_lshl_add_u64 v[110:111], v[198:199], 4, s[48:49]
	v_add_f32_e32 v106, v106, v107
	v_fmamk_f32 v106, v106, 0x3a800000, v238
	v_rsq_f32_e32 v208, v106
	ds_read_b128 v[132:135], v251 offset:2816
	v_pk_mul_f32 v[138:139], v[102:103], v[208:209] op_sel_hi:[1,0]
	v_lshl_add_u64 v[102:103], v[206:207], 4, s[48:49]
	ds_read_b128 v[112:115], v251 offset:2048
	v_lshl_add_u64 v[102:103], v[204:205], 4, s[48:49]
	ds_read_b128 v[106:109], v251 offset:2304
	v_lshl_add_u64 v[102:103], v[200:201], 4, s[48:49]
	v_pk_mul_f32 v[140:141], v[104:105], v[208:209] op_sel_hi:[1,0]
	ds_read_b128 v[102:105], v251 offset:2560
	v_pk_mul_f32 v[56:57], v[56:57], v[208:209] op_sel_hi:[1,0]
	v_pk_mul_f32 v[54:55], v[54:55], v[208:209] op_sel_hi:[1,0]
	s_waitcnt lgkmcnt(0)
	s_load_dwordx4 s[28:31], s[0:1], 0x68
	v_mov_b32_e32 v110, v133
	v_mov_b32_e32 v111, v134
	v_mov_b32_e32 v133, v135
	v_pk_add_f32 v[110:111], v[110:111], v[132:133]
	s_nop 0
	v_add_f32_e32 v110, v110, v111
	v_fmamk_f32 v110, v110, 0x3a800000, v238
	v_rsq_f32_e32 v202, v110
	v_cndmask_b32_e64 v110, 0, 1, s[92:93]
	v_cmp_ne_u32_e64 s[22:23], 1, v110
	v_pk_mul_f32 v[92:93], v[92:93], v[202:203] op_sel_hi:[1,0]
	v_pk_mul_f32 v[90:91], v[90:91], v[202:203] op_sel_hi:[1,0]
	v_pk_mul_f32 v[36:37], v[36:37], v[202:203] op_sel_hi:[1,0]
	v_pk_mul_f32 v[34:35], v[34:35], v[202:203] op_sel_hi:[1,0]
	s_and_saveexec_b64 s[24:25], s[4:5]
	s_cbranch_execz .LBB0_459
	s_and_b64 vcc, exec, s[22:23]
	ds_write_b128 v222, v[138:141]
	ds_write_b128 v222, v[54:57] offset:16
	ds_write_b128 v223, v[90:93]
	ds_write_b128 v222, v[34:37] offset:2064
	s_cbranch_vccnz .LBB0_459
	v_readlane_b32 s68, v254, 9
	v_readlane_b32 s69, v254, 10
	v_lshl_add_u32 v132, s73, 1, v224
	v_ashrrev_i32_e32 v213, 31, v212
	v_mov_b64_e32 v[110:111], s[68:69]
	s_movk_i32 s68, 0x2c00
	v_mad_i64_i32 v[110:111], s[68:69], v132, s68, v[110:111]
	v_lshl_add_u64 v[110:111], v[212:213], 2, v[110:111]
	global_store_dwordx4 v[110:111], v[90:93], off
	global_store_dwordx4 v[110:111], v[34:37], off offset:16
